# nt hint also on the q/k/v special-tile stores of gemm_in (all gemm_in epilogue dwordx4 stores) + act stores
# baseline (speedup 1.0000x reference)
.LBB0_451:
	v_readlane_b32 s20, v237, 49
	v_lshlrev_b32_e32 v0, 6, v4
	v_readlane_b32 s23, v237, 52
	v_readlane_b32 s25, v237, 54
	v_cmp_eq_u32_e64 s[4:5], 23, v135
	v_and_b32_e32 v5, 64, v0
	v_readlane_b32 s22, v237, 51
	v_readlane_b32 s24, v237, 53
	v_mov_b32_e32 v0, s25
	v_mov_b32_e32 v3, s23
	v_cndmask_b32_e64 v7, v0, v3, s[4:5]
	v_mov_b32_e32 v0, s24
	v_mov_b32_e32 v3, s22
	v_cndmask_b32_e64 v6, v0, v3, s[4:5]
	v_lshrrev_b32_e32 v0, 4, v136
	v_ashrrev_i32_e32 v2, 1, v4
	v_and_b32_e32 v0, 0xffffffe, v0
	v_lshlrev_b64 v[8:9], 6, v[0:1]
	v_ashrrev_i32_e32 v3, 31, v2
	v_lshl_add_u64 v[2:3], v[8:9], 0, v[2:3]
	s_movk_i32 s18, 0x2080
	v_mad_u64_u32 v[6:7], s[4:5], v2, s18, v[6:7]
	s_movk_i32 s4, 0xf80
	s_nop 0
	v_and_or_b32 v0, v34, s4, v5
	v_mad_i32_i24 v7, v3, s18, v7
	v_lshlrev_b32_e32 v0, 1, v0
	v_lshl_add_u64 v[2:3], v[6:7], 0, v[0:1]
	v_and_b32_e32 v0, -2, v4
	s_movk_i32 s4, 0x110
	v_mad_u32_u24 v0, v5, s4, v0
	ds_read_u16 v5, v0
	ds_read_u16 v6, v0 offset:272
	v_readlane_b32 s21, v237, 50
	v_readlane_b32 s26, v237, 55
	v_readlane_b32 s27, v237, 56
	s_movk_i32 s94, 0x2080
	s_waitcnt lgkmcnt(0)
	v_lshl_or_b32 v6, v6, 16, v5
	ds_read_u16 v5, v0 offset:544
	ds_read_u16 v7, v0 offset:816
	s_andn2_b64 s[14:15], s[14:15], exec
	s_andn2_b64 s[12:13], s[12:13], exec
	s_waitcnt lgkmcnt(0)
	v_lshl_or_b32 v7, v7, 16, v5
	ds_read_u16 v5, v0 offset:1088
	ds_read_u16 v8, v0 offset:1360
	s_waitcnt lgkmcnt(0)
	v_lshl_or_b32 v8, v8, 16, v5
	ds_read_u16 v5, v0 offset:1632
	ds_read_u16 v9, v0 offset:1904
	s_waitcnt lgkmcnt(0)
	v_lshl_or_b32 v9, v9, 16, v5
	global_store_dwordx4 v[2:3], v[6:9], off nt
	ds_read_u16 v5, v0 offset:2176
	ds_read_u16 v6, v0 offset:2448
	s_waitcnt lgkmcnt(0)
	v_lshl_or_b32 v6, v6, 16, v5
	ds_read_u16 v5, v0 offset:2720
	ds_read_u16 v7, v0 offset:2992
	s_waitcnt lgkmcnt(0)
	v_lshl_or_b32 v7, v7, 16, v5
	ds_read_u16 v5, v0 offset:3264
	ds_read_u16 v8, v0 offset:3536
	s_waitcnt lgkmcnt(0)
	v_lshl_or_b32 v8, v8, 16, v5
	ds_read_u16 v5, v0 offset:3808
	ds_read_u16 v9, v0 offset:4080
	s_waitcnt lgkmcnt(0)
	v_lshl_or_b32 v9, v9, 16, v5
	global_store_dwordx4 v[2:3], v[6:9], off offset:16 nt
	ds_read_u16 v5, v0 offset:4352
	ds_read_u16 v6, v0 offset:4624
	s_waitcnt lgkmcnt(0)
	v_lshl_or_b32 v6, v6, 16, v5
	ds_read_u16 v5, v0 offset:4896
	ds_read_u16 v7, v0 offset:5168
	s_waitcnt lgkmcnt(0)
	v_lshl_or_b32 v7, v7, 16, v5
	ds_read_u16 v5, v0 offset:5440
	ds_read_u16 v8, v0 offset:5712
	s_waitcnt lgkmcnt(0)
	v_lshl_or_b32 v8, v8, 16, v5
	ds_read_u16 v5, v0 offset:5984
	ds_read_u16 v9, v0 offset:6256
	s_waitcnt lgkmcnt(0)
	v_lshl_or_b32 v9, v9, 16, v5
	global_store_dwordx4 v[2:3], v[6:9], off offset:32 nt
	ds_read_u16 v5, v0 offset:6528
	ds_read_u16 v6, v0 offset:6800
	s_waitcnt lgkmcnt(0)
	v_lshl_or_b32 v6, v6, 16, v5
	ds_read_u16 v5, v0 offset:7072
	ds_read_u16 v7, v0 offset:7344
	s_waitcnt lgkmcnt(0)
	v_lshl_or_b32 v7, v7, 16, v5
	ds_read_u16 v5, v0 offset:7616
	ds_read_u16 v8, v0 offset:7888
	s_waitcnt lgkmcnt(0)
	v_lshl_or_b32 v8, v8, 16, v5
	ds_read_u16 v5, v0 offset:8160
	ds_read_u16 v9, v0 offset:8432
	s_waitcnt lgkmcnt(0)
	v_lshl_or_b32 v9, v9, 16, v5
	global_store_dwordx4 v[2:3], v[6:9], off offset:48 nt
	ds_read_u16 v5, v0 offset:8704
	ds_read_u16 v6, v0 offset:8976
	s_waitcnt lgkmcnt(0)
	v_lshl_or_b32 v6, v6, 16, v5
	ds_read_u16 v5, v0 offset:9248
	ds_read_u16 v7, v0 offset:9520
	s_waitcnt lgkmcnt(0)
	v_lshl_or_b32 v7, v7, 16, v5
	ds_read_u16 v5, v0 offset:9792
	ds_read_u16 v8, v0 offset:10064
	s_waitcnt lgkmcnt(0)
	v_lshl_or_b32 v8, v8, 16, v5
	ds_read_u16 v5, v0 offset:10336
	ds_read_u16 v9, v0 offset:10608
	s_waitcnt lgkmcnt(0)
	v_lshl_or_b32 v9, v9, 16, v5
	global_store_dwordx4 v[2:3], v[6:9], off offset:64 nt
	ds_read_u16 v5, v0 offset:10880
	ds_read_u16 v6, v0 offset:11152
	s_waitcnt lgkmcnt(0)
	v_lshl_or_b32 v6, v6, 16, v5
	ds_read_u16 v5, v0 offset:11424
	ds_read_u16 v7, v0 offset:11696
	s_waitcnt lgkmcnt(0)
	v_lshl_or_b32 v7, v7, 16, v5
	ds_read_u16 v5, v0 offset:11968
	ds_read_u16 v8, v0 offset:12240
	s_waitcnt lgkmcnt(0)
	v_lshl_or_b32 v8, v8, 16, v5
	ds_read_u16 v5, v0 offset:12512
	ds_read_u16 v9, v0 offset:12784
	s_waitcnt lgkmcnt(0)
	v_lshl_or_b32 v9, v9, 16, v5
	global_store_dwordx4 v[2:3], v[6:9], off offset:80 nt
	ds_read_u16 v5, v0 offset:13056
	ds_read_u16 v6, v0 offset:13328
	s_waitcnt lgkmcnt(0)
	v_lshl_or_b32 v6, v6, 16, v5
	ds_read_u16 v5, v0 offset:13600
	ds_read_u16 v7, v0 offset:13872
	s_waitcnt lgkmcnt(0)
	v_lshl_or_b32 v7, v7, 16, v5
	ds_read_u16 v5, v0 offset:14144
	ds_read_u16 v8, v0 offset:14416
	s_waitcnt lgkmcnt(0)
	v_lshl_or_b32 v8, v8, 16, v5
	ds_read_u16 v5, v0 offset:14688
	ds_read_u16 v9, v0 offset:14960
	s_waitcnt lgkmcnt(0)
	v_lshl_or_b32 v9, v9, 16, v5
	global_store_dwordx4 v[2:3], v[6:9], off offset:96 nt
	ds_read_u16 v5, v0 offset:15232
	ds_read_u16 v6, v0 offset:15504
	s_waitcnt lgkmcnt(0)
	v_lshl_or_b32 v6, v6, 16, v5
	ds_read_u16 v5, v0 offset:15776
	ds_read_u16 v7, v0 offset:16048
	s_waitcnt lgkmcnt(0)
	v_lshl_or_b32 v7, v7, 16, v5
	ds_read_u16 v5, v0 offset:16320
	ds_read_u16 v8, v0 offset:16592
	s_waitcnt lgkmcnt(0)
	v_lshl_or_b32 v8, v8, 16, v5
	ds_read_u16 v5, v0 offset:16864
	ds_read_u16 v0, v0 offset:17136
	s_waitcnt lgkmcnt(0)
	v_lshl_or_b32 v9, v0, 16, v5
	global_store_dwordx4 v[2:3], v[6:9], off offset:112 nt
	s_or_b64 exec, exec, s[16:17]
	s_and_saveexec_b64 s[16:17], s[12:13]
	s_cbranch_execz .LBB0_439
